# v18: v16 with the P4 relu^2 epilogue hand-written (v_pk_mul_f32 squares, SGPR-base + 32-bit offset stores, 283 instead of 380 instructions per tile)
# baseline (speedup 1.0000x reference)
; #define PG8_STAGE(bufoff, gbase, voff) do { _Pragma("unroll") for (int _i = 0; _i < 2; ++_i) \
;         __builtin_amdgcn_global_load_lds((const unsigned*)((const char*)(gbase) + (voff)[_i]), (LAS unsigned*)(lds + (bufoff) + ldsw + _i * 8192), 16, 0, 0); } while (0)
; #define PG8_LDA(dst, b, h) do { _Pragma("unroll") for (int m = 0; m < 4; ++m) _Pragma("unroll") for (int k = 0; k < 2; ++k) dst[m][k] = *(const LAS bf16x8*)(lds + PG8_SA(b, h) + aoff + m * 2048 + k * 1024); } while (0)
; #define PG8_LDB(dst, b, h) do { _Pragma("unroll") for (int n = 0; n < 2; ++n) _Pragma("unroll") for (int k = 0; k < 2; ++k) dst[n][k] = *(const LAS bf16x8*)(lds + PG8_SB(b, h) + boff + n * 2048 + k * 1024); } while (0)
; #define PG8_MMA(ai, bj, At, Bt) do { __builtin_amdgcn_s_setprio(1); _Pragma("unroll") for (int m = 0; m < 4; ++m) _Pragma("unroll") for (int n = 0; n < 2; ++n) _Pragma("unroll") for (int k = 0; k < 2; ++k) \
;         acc[ai][bj][m][n] = __builtin_amdgcn_mfma_f32_16x16x32_bf16(Bt[n][k], At[m][k], acc[ai][bj][m][n], 0, 0, 0); __builtin_amdgcn_s_setprio(0); } while (0)
; #define PG8_WAIT_V(n) asm volatile("s_waitcnt vmcnt(" #n ")" ::: "memory")
; #define PG8_WAIT_L(n) asm volatile("s_waitcnt lgkmcnt(" #n ")" ::: "memory")
; #define PG8_BAR __builtin_amdgcn_s_barrier()
; #define PG8_SCHED __builtin_amdgcn_sched_barrier(0)
; template <class Epi, class Ptrs>
; __device__ __forceinline__ void gemm_phase(LAS unsigned char* lds, const int K, const StaticOrder& S, const Ptrs& P, const Epi& E) {
;     ...
;             const char* a1 = cA + (size_t)(t + 1) * kstep;
;             const char* a2 = last ? nA : cA + (size_t)(t + 2) * kstep; const char* b2 = last ? nB : cB + (size_t)(t + 2) * kstep;
;             const char* a3 = a2 + kstep; const char* b3 = b2 + kstep;
;             PG8_LDB(B0, 0, 0); PG8_SCHED; PG8_LDA(At, 0, 0); PG8_STAGE(PG8_SA(1, 1), a1 + hstep, voffA);
;             PG8_WAIT_L(8); PG8_BAR; PG8_WAIT_L(0); PG8_MMA(0, 0, At, B0); PG8_BAR; PG8_SCHED;
;             PG8_LDB(B1, 0, 1); PG8_STAGE(PG8_SB(0, 0), b2, voffB);
;             PG8_BAR; PG8_WAIT_L(0); PG8_MMA(0, 1, At, B1); PG8_BAR;
;             PG8_LDA(At, 0, 1); PG8_STAGE(PG8_SA(0, 0), a2, voffA);
;             PG8_BAR; PG8_WAIT_L(0); PG8_MMA(1, 0, At, B0); PG8_BAR; PG8_SCHED;
;             PG8_STAGE(PG8_SB(0, 1), b2 + hstep, voffB);
;             PG8_WAIT_V(6); PG8_BAR; PG8_MMA(1, 1, At, B1); PG8_BAR;
.LBB0_433:
	ds_read_b128 v[152:155], v149
	ds_read_b128 v[156:159], v149 offset:1024
	ds_read_b128 v[160:163], v149 offset:2048
	ds_read_b128 v[164:167], v149 offset:3072
	s_add_u32 s42, s40, 0xfffc0080
	s_addc_u32 s43, s41, -1
	s_cmp_eq_u32 s70, 12
	s_cselect_b32 s45, s1, s43
	s_cselect_b32 s44, s0, s42
	s_cselect_b32 s43, s37, s25
	s_cselect_b32 s42, s36, s23
	s_add_i32 m0, s39, 0xc000
	ds_read_b128 v[168:171], v150
	ds_read_b128 v[172:175], v150 offset:1024
	ds_read_b128 v[176:179], v150 offset:2048
	ds_read_b128 v[180:183], v150 offset:3072
	ds_read_b128 v[184:187], v150 offset:4096
	ds_read_b128 v[188:191], v150 offset:5120
	ds_read_b128 v[192:195], v150 offset:6144
	ds_read_b128 v[196:199], v150 offset:7168
	global_load_lds_dwordx4 v136, s[40:41]
	s_add_i32 m0, s39, 0xe000
	s_nop 0
	global_load_lds_dwordx4 v138, s[40:41]
	s_waitcnt lgkmcnt(8)
	s_barrier
	s_waitcnt lgkmcnt(0)
	v_mfma_f32_16x16x32_bf16 v[124:127], v[152:155], v[168:171], v[124:127]
	v_mfma_f32_16x16x32_bf16 v[124:127], v[156:159], v[172:175], v[124:127]
	v_mfma_f32_16x16x32_bf16 v[120:123], v[164:167], v[172:175], v[120:123]
	v_mfma_f32_16x16x32_bf16 v[120:123], v[160:163], v[168:171], v[120:123]
	v_mfma_f32_16x16x32_bf16 v[104:107], v[160:163], v[176:179], v[104:107]
	v_mfma_f32_16x16x32_bf16 v[104:107], v[164:167], v[180:183], v[104:107]
	v_mfma_f32_16x16x32_bf16 v[108:111], v[156:159], v[180:183], v[108:111]
	v_mfma_f32_16x16x32_bf16 v[108:111], v[152:155], v[176:179], v[108:111]
	v_mfma_f32_16x16x32_bf16 v[92:95], v[152:155], v[184:187], v[92:95]
	v_mfma_f32_16x16x32_bf16 v[92:95], v[156:159], v[188:191], v[92:95]
	v_mfma_f32_16x16x32_bf16 v[88:91], v[164:167], v[188:191], v[88:91]
	v_mfma_f32_16x16x32_bf16 v[88:91], v[160:163], v[184:187], v[88:91]
	v_mfma_f32_16x16x32_bf16 v[72:75], v[160:163], v[192:195], v[72:75]
	v_mfma_f32_16x16x32_bf16 v[72:75], v[164:167], v[196:199], v[72:75]
	v_mfma_f32_16x16x32_bf16 v[76:79], v[156:159], v[196:199], v[76:79]
	v_mfma_f32_16x16x32_bf16 v[76:79], v[152:155], v[192:195], v[76:79]
	s_barrier
	s_add_i32 s71, s63, s51
	s_add_u32 s76, s42, 0x80
	s_addc_u32 s77, s43, 0
	s_mov_b32 m0, s71
	ds_read_b128 v[200:203], v151
	ds_read_b128 v[204:207], v151 offset:1024
	ds_read_b128 v[210:213], v151 offset:2048
	ds_read_b128 v[214:217], v151 offset:3072
	global_load_lds_dwordx4 v130, s[42:43]
	s_add_i32 m0, s71, 0x2000
	s_nop 0
	global_load_lds_dwordx4 v134, s[42:43]
	s_barrier
	s_waitcnt lgkmcnt(0)
	v_mfma_f32_16x16x32_bf16 v[116:119], v[200:203], v[168:171], v[116:119]
	v_mfma_f32_16x16x32_bf16 v[116:119], v[204:207], v[172:175], v[116:119]
	v_mfma_f32_16x16x32_bf16 v[112:115], v[214:217], v[172:175], v[112:115]
	v_mfma_f32_16x16x32_bf16 v[112:115], v[210:213], v[168:171], v[112:115]
	v_mfma_f32_16x16x32_bf16 v[96:99], v[210:213], v[176:179], v[96:99]
	v_mfma_f32_16x16x32_bf16 v[96:99], v[214:217], v[180:183], v[96:99]
	v_mfma_f32_16x16x32_bf16 v[100:103], v[204:207], v[180:183], v[100:103]
	v_mfma_f32_16x16x32_bf16 v[100:103], v[200:203], v[176:179], v[100:103]
	v_mfma_f32_16x16x32_bf16 v[84:87], v[200:203], v[184:187], v[84:87]
	v_mfma_f32_16x16x32_bf16 v[84:87], v[204:207], v[188:191], v[84:87]
	v_mfma_f32_16x16x32_bf16 v[80:83], v[214:217], v[188:191], v[80:83]
	v_mfma_f32_16x16x32_bf16 v[80:83], v[210:213], v[184:187], v[80:83]
	v_mfma_f32_16x16x32_bf16 v[64:67], v[210:213], v[192:195], v[64:67]
	v_mfma_f32_16x16x32_bf16 v[64:67], v[214:217], v[196:199], v[64:67]
	v_mfma_f32_16x16x32_bf16 v[68:71], v[204:207], v[196:199], v[68:71]
	v_mfma_f32_16x16x32_bf16 v[68:71], v[200:203], v[192:195], v[68:71]
	s_barrier
	s_mov_b32 m0, s39
	s_add_u32 s78, s44, 0x80
	s_addc_u32 s79, s45, 0
	ds_read_b128 v[168:171], v150 offset:16384
	ds_read_b128 v[172:175], v150 offset:17408
	ds_read_b128 v[176:179], v150 offset:18432
	ds_read_b128 v[180:183], v150 offset:19456
	ds_read_b128 v[184:187], v150 offset:20480
	ds_read_b128 v[188:191], v150 offset:21504
	ds_read_b128 v[192:195], v150 offset:22528
	ds_read_b128 v[196:199], v150 offset:23552
	global_load_lds_dwordx4 v128, s[44:45]
	s_mov_b32 m0, s56
	s_nop 0
	global_load_lds_dwordx4 v132, s[44:45]
	s_barrier
	s_waitcnt lgkmcnt(0)
	v_mfma_f32_16x16x32_bf16 v[60:63], v[152:155], v[168:171], v[60:63]
	v_mfma_f32_16x16x32_bf16 v[60:63], v[156:159], v[172:175], v[60:63]
	v_mfma_f32_16x16x32_bf16 v[56:59], v[164:167], v[172:175], v[56:59]
	v_mfma_f32_16x16x32_bf16 v[56:59], v[160:163], v[168:171], v[56:59]
	v_mfma_f32_16x16x32_bf16 v[40:43], v[160:163], v[176:179], v[40:43]
	v_mfma_f32_16x16x32_bf16 v[40:43], v[164:167], v[180:183], v[40:43]
	v_mfma_f32_16x16x32_bf16 v[44:47], v[156:159], v[180:183], v[44:47]
	v_mfma_f32_16x16x32_bf16 v[44:47], v[152:155], v[176:179], v[44:47]
	v_mfma_f32_16x16x32_bf16 v[28:31], v[152:155], v[184:187], v[28:31]
	v_mfma_f32_16x16x32_bf16 v[28:31], v[156:159], v[188:191], v[28:31]
	v_mfma_f32_16x16x32_bf16 v[24:27], v[164:167], v[188:191], v[24:27]
	v_mfma_f32_16x16x32_bf16 v[24:27], v[160:163], v[184:187], v[24:27]
	v_mfma_f32_16x16x32_bf16 v[8:11], v[160:163], v[192:195], v[8:11]
	v_mfma_f32_16x16x32_bf16 v[8:11], v[164:167], v[196:199], v[8:11]
	v_mfma_f32_16x16x32_bf16 v[12:15], v[156:159], v[196:199], v[12:15]
	v_mfma_f32_16x16x32_bf16 v[12:15], v[152:155], v[192:195], v[12:15]
	s_barrier
	s_add_u32 s72, s42, 0x40000
	s_addc_u32 s73, s43, 0
	s_add_i32 s71, s64, s51
	s_mov_b32 m0, s71
	s_nop 0
	global_load_lds_dwordx4 v130, s[72:73]
	s_add_i32 m0, s71, 0x2000
	s_nop 0
	global_load_lds_dwordx4 v134, s[72:73]
	s_waitcnt vmcnt(6)
	s_barrier
; #define PG8_STAGE(bufoff, gbase, voff) do { _Pragma("unroll") for (int _i = 0; _i < 2; ++_i) \
;         __builtin_amdgcn_global_load_lds((const unsigned*)((const char*)(gbase) + (voff)[_i]), (LAS unsigned*)(lds + (bufoff) + ldsw + _i * 8192), 16, 0, 0); } while (0)
; #define PG8_LDA(dst, b, h) do { _Pragma("unroll") for (int m = 0; m < 4; ++m) _Pragma("unroll") for (int k = 0; k < 2; ++k) dst[m][k] = *(const LAS bf16x8*)(lds + PG8_SA(b, h) + aoff + m * 2048 + k * 1024); } while (0)
; #define PG8_LDB(dst, b, h) do { _Pragma("unroll") for (int n = 0; n < 2; ++n) _Pragma("unroll") for (int k = 0; k < 2; ++k) dst[n][k] = *(const LAS bf16x8*)(lds + PG8_SB(b, h) + boff + n * 2048 + k * 1024); } while (0)
; #define PG8_MMA(ai, bj, At, Bt) do { __builtin_amdgcn_s_setprio(1); _Pragma("unroll") for (int m = 0; m < 4; ++m) _Pragma("unroll") for (int n = 0; n < 2; ++n) _Pragma("unroll") for (int k = 0; k < 2; ++k) \
;         acc[ai][bj][m][n] = __builtin_amdgcn_mfma_f32_16x16x32_bf16(Bt[n][k], At[m][k], acc[ai][bj][m][n], 0, 0, 0); __builtin_amdgcn_s_setprio(0); } while (0)
; #define PG8_WAIT_V(n) asm volatile("s_waitcnt vmcnt(" #n ")" ::: "memory")
; #define PG8_WAIT_L(n) asm volatile("s_waitcnt lgkmcnt(" #n ")" ::: "memory")
; #define PG8_BAR __builtin_amdgcn_s_barrier()
; #define PG8_SCHED __builtin_amdgcn_sched_barrier(0)
; template <class Epi, class Ptrs>
; __device__ __forceinline__ void gemm_phase(LAS unsigned char* lds, const int K, const StaticOrder& S, const Ptrs& P, const Epi& E) {
;     ...
;             PG8_WAIT_V(6); PG8_BAR; PG8_MMA(1, 1, At, B1); PG8_BAR;
;             PG8_LDB(B0, 1, 0); PG8_SCHED; PG8_LDA(At, 1, 0); PG8_STAGE(PG8_SA(0, 1), a2 + hstep, voffA);
;             PG8_WAIT_L(8); PG8_BAR; PG8_WAIT_L(0); PG8_MMA(0, 0, At, B0); PG8_BAR; PG8_SCHED;
;             PG8_LDB(B1, 1, 1); PG8_STAGE(PG8_SB(1, 0), b3, voffB);
;             PG8_BAR; PG8_WAIT_L(0); PG8_MMA(0, 1, At, B1); PG8_BAR;
;             PG8_LDA(At, 1, 1); PG8_STAGE(PG8_SA(1, 0), a3, voffA);
;             PG8_BAR; PG8_WAIT_L(0); PG8_MMA(1, 0, At, B0); PG8_BAR; PG8_SCHED;
;             PG8_STAGE(PG8_SB(1, 1), b3 + hstep, voffB);
	v_mfma_f32_16x16x32_bf16 v[52:55], v[200:203], v[168:171], v[52:55]
	v_mfma_f32_16x16x32_bf16 v[52:55], v[204:207], v[172:175], v[52:55]
	v_mfma_f32_16x16x32_bf16 v[48:51], v[214:217], v[172:175], v[48:51]
	v_mfma_f32_16x16x32_bf16 v[48:51], v[210:213], v[168:171], v[48:51]
	v_mfma_f32_16x16x32_bf16 v[32:35], v[210:213], v[176:179], v[32:35]
	v_mfma_f32_16x16x32_bf16 v[32:35], v[214:217], v[180:183], v[32:35]
	v_mfma_f32_16x16x32_bf16 v[36:39], v[204:207], v[180:183], v[36:39]
	v_mfma_f32_16x16x32_bf16 v[36:39], v[200:203], v[176:179], v[36:39]
	v_mfma_f32_16x16x32_bf16 v[20:23], v[200:203], v[184:187], v[20:23]
	v_mfma_f32_16x16x32_bf16 v[20:23], v[204:207], v[188:191], v[20:23]
	v_mfma_f32_16x16x32_bf16 v[16:19], v[214:217], v[188:191], v[16:19]
	v_mfma_f32_16x16x32_bf16 v[16:19], v[210:213], v[184:187], v[16:19]
	v_mfma_f32_16x16x32_bf16 v[0:3], v[210:213], v[192:195], v[0:3]
	v_mfma_f32_16x16x32_bf16 v[0:3], v[214:217], v[196:199], v[0:3]
	v_mfma_f32_16x16x32_bf16 v[4:7], v[204:207], v[196:199], v[4:7]
	v_mfma_f32_16x16x32_bf16 v[4:7], v[200:203], v[192:195], v[4:7]
	s_barrier
	s_add_i32 s71, 0, 0x18000
	ds_read_b128 v[152:155], v252
	ds_read_b128 v[156:159], v252 offset:1024
	ds_read_b128 v[160:163], v252 offset:2048
	ds_read_b128 v[164:167], v252 offset:3072
	s_add_u32 s44, s44, 0x40000
	s_addc_u32 s45, s45, 0
	s_mov_b32 m0, s57
	ds_read_b128 v[168:171], v150 offset:32768
	ds_read_b128 v[172:175], v150 offset:33792
	ds_read_b128 v[176:179], v150 offset:34816
	ds_read_b128 v[180:183], v150 offset:35840
	ds_read_b128 v[184:187], v150 offset:36864
	ds_read_b128 v[188:191], v150 offset:37888
	ds_read_b128 v[192:195], v150 offset:38912
	ds_read_b128 v[196:199], v150 offset:39936
	global_load_lds_dwordx4 v128, s[44:45]
	s_mov_b32 m0, s58
	s_nop 0
	global_load_lds_dwordx4 v132, s[44:45]
	s_waitcnt lgkmcnt(8)
	s_barrier
	s_waitcnt lgkmcnt(0)
	v_mfma_f32_16x16x32_bf16 v[124:127], v[152:155], v[168:171], v[124:127]
	v_mfma_f32_16x16x32_bf16 v[124:127], v[156:159], v[172:175], v[124:127]
	v_mfma_f32_16x16x32_bf16 v[120:123], v[164:167], v[172:175], v[120:123]
	v_mfma_f32_16x16x32_bf16 v[120:123], v[160:163], v[168:171], v[120:123]
	v_mfma_f32_16x16x32_bf16 v[104:107], v[160:163], v[176:179], v[104:107]
	v_mfma_f32_16x16x32_bf16 v[104:107], v[164:167], v[180:183], v[104:107]
	v_mfma_f32_16x16x32_bf16 v[108:111], v[156:159], v[180:183], v[108:111]
	v_mfma_f32_16x16x32_bf16 v[108:111], v[152:155], v[176:179], v[108:111]
	v_mfma_f32_16x16x32_bf16 v[92:95], v[152:155], v[184:187], v[92:95]
	v_mfma_f32_16x16x32_bf16 v[92:95], v[156:159], v[188:191], v[92:95]
	v_mfma_f32_16x16x32_bf16 v[88:91], v[164:167], v[188:191], v[88:91]
	v_mfma_f32_16x16x32_bf16 v[88:91], v[160:163], v[184:187], v[88:91]
	v_mfma_f32_16x16x32_bf16 v[72:75], v[160:163], v[192:195], v[72:75]
	v_mfma_f32_16x16x32_bf16 v[72:75], v[164:167], v[196:199], v[72:75]
	v_mfma_f32_16x16x32_bf16 v[76:79], v[156:159], v[196:199], v[76:79]
	v_mfma_f32_16x16x32_bf16 v[76:79], v[152:155], v[192:195], v[76:79]
	s_barrier
	s_add_i32 s44, 0, 0x1c000
	s_add_i32 s45, s71, s51
	s_mov_b32 m0, s45
	ds_read_b128 v[200:203], v253
	ds_read_b128 v[204:207], v253 offset:1024
	ds_read_b128 v[210:213], v253 offset:2048
	ds_read_b128 v[214:217], v253 offset:3072
	global_load_lds_dwordx4 v130, s[76:77]
	s_add_i32 m0, s45, 0x2000
	s_nop 0
	global_load_lds_dwordx4 v134, s[76:77]
	s_barrier
	s_waitcnt lgkmcnt(0)
	v_mfma_f32_16x16x32_bf16 v[116:119], v[200:203], v[168:171], v[116:119]
	v_mfma_f32_16x16x32_bf16 v[116:119], v[204:207], v[172:175], v[116:119]
	v_mfma_f32_16x16x32_bf16 v[112:115], v[214:217], v[172:175], v[112:115]
	v_mfma_f32_16x16x32_bf16 v[112:115], v[210:213], v[168:171], v[112:115]
	v_mfma_f32_16x16x32_bf16 v[96:99], v[210:213], v[176:179], v[96:99]
	v_mfma_f32_16x16x32_bf16 v[96:99], v[214:217], v[180:183], v[96:99]
	v_mfma_f32_16x16x32_bf16 v[100:103], v[204:207], v[180:183], v[100:103]
	v_mfma_f32_16x16x32_bf16 v[100:103], v[200:203], v[176:179], v[100:103]
	v_mfma_f32_16x16x32_bf16 v[84:87], v[200:203], v[184:187], v[84:87]
	v_mfma_f32_16x16x32_bf16 v[84:87], v[204:207], v[188:191], v[84:87]
	v_mfma_f32_16x16x32_bf16 v[80:83], v[214:217], v[188:191], v[80:83]
	v_mfma_f32_16x16x32_bf16 v[80:83], v[210:213], v[184:187], v[80:83]
	v_mfma_f32_16x16x32_bf16 v[64:67], v[210:213], v[192:195], v[64:67]
	v_mfma_f32_16x16x32_bf16 v[64:67], v[214:217], v[196:199], v[64:67]
	v_mfma_f32_16x16x32_bf16 v[68:71], v[204:207], v[196:199], v[68:71]
	v_mfma_f32_16x16x32_bf16 v[68:71], v[200:203], v[192:195], v[68:71]
	s_barrier
	s_mov_b32 m0, s61
	ds_read_b128 v[168:171], v150 offset:49152
	ds_read_b128 v[172:175], v150 offset:50176
	ds_read_b128 v[176:179], v150 offset:51200
	ds_read_b128 v[180:183], v150 offset:52224
	ds_read_b128 v[184:187], v150 offset:53248
	ds_read_b128 v[188:191], v150 offset:54272
	ds_read_b128 v[192:195], v150 offset:55296
	ds_read_b128 v[196:199], v150 offset:56320
	global_load_lds_dwordx4 v128, s[78:79]
	s_mov_b32 m0, s62
	s_nop 0
	global_load_lds_dwordx4 v132, s[78:79]
	s_barrier
	s_waitcnt lgkmcnt(0)
	v_mfma_f32_16x16x32_bf16 v[60:63], v[152:155], v[168:171], v[60:63]
	v_mfma_f32_16x16x32_bf16 v[60:63], v[156:159], v[172:175], v[60:63]
	v_mfma_f32_16x16x32_bf16 v[56:59], v[164:167], v[172:175], v[56:59]
	v_mfma_f32_16x16x32_bf16 v[56:59], v[160:163], v[168:171], v[56:59]
	v_mfma_f32_16x16x32_bf16 v[40:43], v[160:163], v[176:179], v[40:43]
	v_mfma_f32_16x16x32_bf16 v[40:43], v[164:167], v[180:183], v[40:43]
	v_mfma_f32_16x16x32_bf16 v[44:47], v[156:159], v[180:183], v[44:47]
	v_mfma_f32_16x16x32_bf16 v[44:47], v[152:155], v[176:179], v[44:47]
	v_mfma_f32_16x16x32_bf16 v[28:31], v[152:155], v[184:187], v[28:31]
	v_mfma_f32_16x16x32_bf16 v[28:31], v[156:159], v[188:191], v[28:31]
	v_mfma_f32_16x16x32_bf16 v[24:27], v[164:167], v[188:191], v[24:27]
	v_mfma_f32_16x16x32_bf16 v[24:27], v[160:163], v[184:187], v[24:27]
	v_mfma_f32_16x16x32_bf16 v[8:11], v[160:163], v[192:195], v[8:11]
	v_mfma_f32_16x16x32_bf16 v[8:11], v[164:167], v[196:199], v[8:11]
	v_mfma_f32_16x16x32_bf16 v[12:15], v[156:159], v[196:199], v[12:15]
	v_mfma_f32_16x16x32_bf16 v[12:15], v[152:155], v[192:195], v[12:15]
	s_barrier
; __device__ __forceinline__ unsigned cvt_pk_bf16(float lo, float hi) { unsigned r; asm volatile("v_cvt_pk_bf16_f32 %0, %1, %2" : "=v"(r) : "v"(lo), "v"(hi)); return r; }
; #define PG8_STAGE(bufoff, gbase, voff) do { _Pragma("unroll") for (int _i = 0; _i < 2; ++_i) \
;         __builtin_amdgcn_global_load_lds((const unsigned*)((const char*)(gbase) + (voff)[_i]), (LAS unsigned*)(lds + (bufoff) + ldsw + _i * 8192), 16, 0, 0); } while (0)
; #define PG8_MMA(ai, bj, At, Bt) do { __builtin_amdgcn_s_setprio(1); _Pragma("unroll") for (int m = 0; m < 4; ++m) _Pragma("unroll") for (int n = 0; n < 2; ++n) _Pragma("unroll") for (int k = 0; k < 2; ++k) \
;         acc[ai][bj][m][n] = __builtin_amdgcn_mfma_f32_16x16x32_bf16(Bt[n][k], At[m][k], acc[ai][bj][m][n], 0, 0, 0); __builtin_amdgcn_s_setprio(0); } while (0)
; #define PG8_WAIT_V(n) asm volatile("s_waitcnt vmcnt(" #n ")" ::: "memory")
; #define PG8_BAR __builtin_amdgcn_s_barrier()
; template <class Epi, class Ptrs>
; __device__ __forceinline__ void gemm_phase(LAS unsigned char* lds, const int K, const StaticOrder& S, const Ptrs& P, const Epi& E) {
;     ...
;             PG8_STAGE(PG8_SB(1, 1), b3 + hstep, voffB);
;             PG8_WAIT_V(6); PG8_BAR; PG8_MMA(1, 1, At, B1); PG8_BAR;
;     __device__ __forceinline__ void operator()(const f32x4 (&acc)[2][2][4][2], const Unit& u, int ui, int wr, int wc, int fr, int fq) const {
;         const int row0 = u.pm * 256 + wr * 64 + fr, col0 = u.pn * 256 + wc * 32 + 8 * fq;
; #pragma unroll
;         for (int ai = 0; ai < 2; ++ai)
; #pragma unroll
;             for (int m = 0; m < 4; ++m) { bf16_t* rowp = hid + (size_t)(row0 + ai * 128 + m * 16) * DFF + col0;
; #pragma unroll
;                 for (int bj = 0; bj < 2; ++bj) { f32x4 v0 = acc[ai][bj][m][0], v1 = acc[ai][bj][m][1];
; #pragma unroll
;                     for (int j = 0; j < 4; ++j) { const float a = fmaxf(v0[j], 0.f), b = fmaxf(v1[j], 0.f); v0[j] = a * a; v1[j] = b * b; }
;                     u32x4 w; w.x = cvt_pk_bf16(v0[0], v0[1]); w.y = cvt_pk_bf16(v0[2], v0[3]); w.z = cvt_pk_bf16(v1[0], v1[1]); w.w = cvt_pk_bf16(v1[2], v1[3]);
;                     *(u32x4*)(rowp + bj * 128) = w; } }
	s_add_u32 s42, s42, 0x40080
	s_addc_u32 s43, s43, 0
	s_add_i32 s44, s44, s51
	s_mov_b32 m0, s44
	s_nop 0
	global_load_lds_dwordx4 v130, s[42:43]
	s_add_i32 m0, s44, 0x2000
	s_nop 0
	global_load_lds_dwordx4 v134, s[42:43]
	s_waitcnt vmcnt(6)
	s_barrier
	v_mfma_f32_16x16x32_bf16 v[52:55], v[200:203], v[168:171], v[52:55]
	v_mfma_f32_16x16x32_bf16 v[52:55], v[204:207], v[172:175], v[52:55]
	v_mfma_f32_16x16x32_bf16 v[48:51], v[214:217], v[172:175], v[48:51]
	v_mfma_f32_16x16x32_bf16 v[48:51], v[210:213], v[168:171], v[48:51]
	v_mfma_f32_16x16x32_bf16 v[32:35], v[210:213], v[176:179], v[32:35]
	v_mfma_f32_16x16x32_bf16 v[32:35], v[214:217], v[180:183], v[32:35]
	v_mfma_f32_16x16x32_bf16 v[36:39], v[204:207], v[180:183], v[36:39]
	v_mfma_f32_16x16x32_bf16 v[36:39], v[200:203], v[176:179], v[36:39]
	v_mfma_f32_16x16x32_bf16 v[20:23], v[200:203], v[184:187], v[20:23]
	v_mfma_f32_16x16x32_bf16 v[20:23], v[204:207], v[188:191], v[20:23]
	v_mfma_f32_16x16x32_bf16 v[16:19], v[214:217], v[188:191], v[16:19]
	v_mfma_f32_16x16x32_bf16 v[16:19], v[210:213], v[184:187], v[16:19]
	v_mfma_f32_16x16x32_bf16 v[0:3], v[210:213], v[192:195], v[0:3]
	v_mfma_f32_16x16x32_bf16 v[0:3], v[214:217], v[196:199], v[0:3]
	v_mfma_f32_16x16x32_bf16 v[4:7], v[204:207], v[196:199], v[4:7]
	v_mfma_f32_16x16x32_bf16 v[4:7], v[200:203], v[192:195], v[4:7]
	s_barrier
	s_add_i32 s70, s70, 2
	s_add_u32 s40, s40, 0x100
	s_addc_u32 s41, s41, 0
	s_add_u32 s23, s23, 0x100
	s_addc_u32 s25, s25, 0
	s_cmp_gt_u32 s70, 13
	s_cbranch_scc0 .LBB0_433
	v_lshl_add_u32 v152, s38, 8, v146
	v_lshl_or_b32 v144, s69, 8, v148
	v_lshlrev_b32_e32 v152, 13, v152
	v_lshl_add_u32 v144, v144, 1, v152
	v_add_u32_e32 v145, 0x20000, v144
	v_add_u32_e32 v152, 0x40000, v144
	v_add_u32_e32 v153, 0x60000, v144
	v_add_u32_e32 v154, 0x100000, v144
	v_add_u32_e32 v155, 0x120000, v144
	v_add_u32_e32 v156, 0x140000, v144
	v_add_u32_e32 v157, 0x160000, v144
	s_and_b64 vcc, exec, s[4:5]
	s_mov_b32 s69, s22
	s_mov_b32 s38, s24
	s_mov_b64 s[40:41], s[0:1]
	s_mov_b64 s[42:43], s[36:37]
	v_max_f32_e32 v120, 0, v120
	v_max_f32_e32 v121, 0, v121
	v_max_f32_e32 v122, 0, v122
	v_max_f32_e32 v123, 0, v123
	v_max_f32_e32 v124, 0, v124
	v_max_f32_e32 v125, 0, v125
	v_max_f32_e32 v126, 0, v126
	v_max_f32_e32 v127, 0, v127
	v_pk_mul_f32 v[120:121], v[120:121], v[120:121]
	v_pk_mul_f32 v[122:123], v[122:123], v[122:123]
	v_pk_mul_f32 v[124:125], v[124:125], v[124:125]
	v_pk_mul_f32 v[126:127], v[126:127], v[126:127]
	v_cvt_pk_bf16_f32 v124, v124, v125
	v_cvt_pk_bf16_f32 v125, v126, v127
	v_cvt_pk_bf16_f32 v126, v120, v121
	v_cvt_pk_bf16_f32 v127, v122, v123
	global_store_dwordx4 v144, v[124:127], s[10:11]
	v_max_f32_e32 v112, 0, v112
	v_max_f32_e32 v113, 0, v113
	v_max_f32_e32 v114, 0, v114
	v_max_f32_e32 v115, 0, v115
	v_max_f32_e32 v116, 0, v116
	v_max_f32_e32 v117, 0, v117
	v_max_f32_e32 v118, 0, v118
	v_max_f32_e32 v119, 0, v119
	v_pk_mul_f32 v[112:113], v[112:113], v[112:113]
	v_pk_mul_f32 v[114:115], v[114:115], v[114:115]
	v_pk_mul_f32 v[116:117], v[116:117], v[116:117]
	v_pk_mul_f32 v[118:119], v[118:119], v[118:119]
	v_cvt_pk_bf16_f32 v116, v116, v117
	v_cvt_pk_bf16_f32 v117, v118, v119
	v_cvt_pk_bf16_f32 v118, v112, v113
	v_cvt_pk_bf16_f32 v119, v114, v115
	global_store_dwordx4 v144, v[116:119], s[10:11] offset:256
	v_max_f32_e32 v104, 0, v104
	v_max_f32_e32 v105, 0, v105
	v_max_f32_e32 v106, 0, v106
	v_max_f32_e32 v107, 0, v107
	v_max_f32_e32 v108, 0, v108
	v_max_f32_e32 v109, 0, v109
	v_max_f32_e32 v110, 0, v110
	v_max_f32_e32 v111, 0, v111
	v_pk_mul_f32 v[104:105], v[104:105], v[104:105]
	v_pk_mul_f32 v[106:107], v[106:107], v[106:107]
	v_pk_mul_f32 v[108:109], v[108:109], v[108:109]
	v_pk_mul_f32 v[110:111], v[110:111], v[110:111]
	v_cvt_pk_bf16_f32 v108, v108, v109
	v_cvt_pk_bf16_f32 v109, v110, v111
	v_cvt_pk_bf16_f32 v110, v104, v105
	v_cvt_pk_bf16_f32 v111, v106, v107
	global_store_dwordx4 v145, v[108:111], s[10:11]
	v_max_f32_e32 v96, 0, v96
	v_max_f32_e32 v97, 0, v97
	v_max_f32_e32 v98, 0, v98
	v_max_f32_e32 v99, 0, v99
	v_max_f32_e32 v100, 0, v100
	v_max_f32_e32 v101, 0, v101
	v_max_f32_e32 v102, 0, v102
	v_max_f32_e32 v103, 0, v103
	v_pk_mul_f32 v[96:97], v[96:97], v[96:97]
	v_pk_mul_f32 v[98:99], v[98:99], v[98:99]
	v_pk_mul_f32 v[100:101], v[100:101], v[100:101]
	v_pk_mul_f32 v[102:103], v[102:103], v[102:103]
	v_cvt_pk_bf16_f32 v100, v100, v101
	v_cvt_pk_bf16_f32 v101, v102, v103
	v_cvt_pk_bf16_f32 v102, v96, v97
	v_cvt_pk_bf16_f32 v103, v98, v99
	global_store_dwordx4 v145, v[100:103], s[10:11] offset:256
	v_max_f32_e32 v88, 0, v88
	v_max_f32_e32 v89, 0, v89
	v_max_f32_e32 v90, 0, v90
	v_max_f32_e32 v91, 0, v91
	v_max_f32_e32 v92, 0, v92
	v_max_f32_e32 v93, 0, v93
	v_max_f32_e32 v94, 0, v94
	v_max_f32_e32 v95, 0, v95
	v_pk_mul_f32 v[88:89], v[88:89], v[88:89]
	v_pk_mul_f32 v[90:91], v[90:91], v[90:91]
	v_pk_mul_f32 v[92:93], v[92:93], v[92:93]
	v_pk_mul_f32 v[94:95], v[94:95], v[94:95]
	v_cvt_pk_bf16_f32 v92, v92, v93
	v_cvt_pk_bf16_f32 v93, v94, v95
	v_cvt_pk_bf16_f32 v94, v88, v89
	v_cvt_pk_bf16_f32 v95, v90, v91
	global_store_dwordx4 v152, v[92:95], s[10:11]
	v_max_f32_e32 v80, 0, v80
	v_max_f32_e32 v81, 0, v81
	v_max_f32_e32 v82, 0, v82
	v_max_f32_e32 v83, 0, v83
	v_max_f32_e32 v84, 0, v84
	v_max_f32_e32 v85, 0, v85
	v_max_f32_e32 v86, 0, v86
	v_max_f32_e32 v87, 0, v87
	v_pk_mul_f32 v[80:81], v[80:81], v[80:81]
	v_pk_mul_f32 v[82:83], v[82:83], v[82:83]
	v_pk_mul_f32 v[84:85], v[84:85], v[84:85]
	v_pk_mul_f32 v[86:87], v[86:87], v[86:87]
	v_cvt_pk_bf16_f32 v84, v84, v85
	v_cvt_pk_bf16_f32 v85, v86, v87
	v_cvt_pk_bf16_f32 v86, v80, v81
	v_cvt_pk_bf16_f32 v87, v82, v83
	global_store_dwordx4 v152, v[84:87], s[10:11] offset:256
; __device__ __forceinline__ unsigned cvt_pk_bf16(float lo, float hi) { unsigned r; asm volatile("v_cvt_pk_bf16_f32 %0, %1, %2" : "=v"(r) : "v"(lo), "v"(hi)); return r; }
;     __device__ __forceinline__ void operator()(const f32x4 (&acc)[2][2][4][2], const Unit& u, int ui, int wr, int wc, int fr, int fq) const {
;     ...
;         for (int ai = 0; ai < 2; ++ai)
; #pragma unroll
;             for (int m = 0; m < 4; ++m) { bf16_t* rowp = hid + (size_t)(row0 + ai * 128 + m * 16) * DFF + col0;
; #pragma unroll
;                 for (int bj = 0; bj < 2; ++bj) { f32x4 v0 = acc[ai][bj][m][0], v1 = acc[ai][bj][m][1];
; #pragma unroll
;                     for (int j = 0; j < 4; ++j) { const float a = fmaxf(v0[j], 0.f), b = fmaxf(v1[j], 0.f); v0[j] = a * a; v1[j] = b * b; }
;                     u32x4 w; w.x = cvt_pk_bf16(v0[0], v0[1]); w.y = cvt_pk_bf16(v0[2], v0[3]); w.z = cvt_pk_bf16(v1[0], v1[1]); w.w = cvt_pk_bf16(v1[2], v1[3]);
;                     *(u32x4*)(rowp + bj * 128) = w; } }
	v_max_f32_e32 v72, 0, v72
	v_max_f32_e32 v73, 0, v73
	v_max_f32_e32 v74, 0, v74
	v_max_f32_e32 v75, 0, v75
	v_max_f32_e32 v76, 0, v76
	v_max_f32_e32 v77, 0, v77
	v_max_f32_e32 v78, 0, v78
	v_max_f32_e32 v79, 0, v79
	v_pk_mul_f32 v[72:73], v[72:73], v[72:73]
	v_pk_mul_f32 v[74:75], v[74:75], v[74:75]
	v_pk_mul_f32 v[76:77], v[76:77], v[76:77]
	v_pk_mul_f32 v[78:79], v[78:79], v[78:79]
	v_cvt_pk_bf16_f32 v76, v76, v77
	v_cvt_pk_bf16_f32 v77, v78, v79
	v_cvt_pk_bf16_f32 v78, v72, v73
	v_cvt_pk_bf16_f32 v79, v74, v75
	global_store_dwordx4 v153, v[76:79], s[10:11]
	v_max_f32_e32 v64, 0, v64
	v_max_f32_e32 v65, 0, v65
	v_max_f32_e32 v66, 0, v66
	v_max_f32_e32 v67, 0, v67
	v_max_f32_e32 v68, 0, v68
	v_max_f32_e32 v69, 0, v69
	v_max_f32_e32 v70, 0, v70
	v_max_f32_e32 v71, 0, v71
	v_pk_mul_f32 v[64:65], v[64:65], v[64:65]
	v_pk_mul_f32 v[66:67], v[66:67], v[66:67]
	v_pk_mul_f32 v[68:69], v[68:69], v[68:69]
	v_pk_mul_f32 v[70:71], v[70:71], v[70:71]
	v_cvt_pk_bf16_f32 v68, v68, v69
	v_cvt_pk_bf16_f32 v69, v70, v71
	v_cvt_pk_bf16_f32 v70, v64, v65
	v_cvt_pk_bf16_f32 v71, v66, v67
	global_store_dwordx4 v153, v[68:71], s[10:11] offset:256
	v_max_f32_e32 v56, 0, v56
	v_max_f32_e32 v57, 0, v57
	v_max_f32_e32 v58, 0, v58
	v_max_f32_e32 v59, 0, v59
	v_max_f32_e32 v60, 0, v60
	v_max_f32_e32 v61, 0, v61
	v_max_f32_e32 v62, 0, v62
	v_max_f32_e32 v63, 0, v63
	v_pk_mul_f32 v[56:57], v[56:57], v[56:57]
	v_pk_mul_f32 v[58:59], v[58:59], v[58:59]
	v_pk_mul_f32 v[60:61], v[60:61], v[60:61]
	v_pk_mul_f32 v[62:63], v[62:63], v[62:63]
	v_cvt_pk_bf16_f32 v60, v60, v61
	v_cvt_pk_bf16_f32 v61, v62, v63
	v_cvt_pk_bf16_f32 v62, v56, v57
	v_cvt_pk_bf16_f32 v63, v58, v59
	global_store_dwordx4 v154, v[60:63], s[10:11]
	v_max_f32_e32 v48, 0, v48
	v_max_f32_e32 v49, 0, v49
	v_max_f32_e32 v50, 0, v50
	v_max_f32_e32 v51, 0, v51
	v_max_f32_e32 v52, 0, v52
	v_max_f32_e32 v53, 0, v53
	v_max_f32_e32 v54, 0, v54
	v_max_f32_e32 v55, 0, v55
	v_pk_mul_f32 v[48:49], v[48:49], v[48:49]
	v_pk_mul_f32 v[50:51], v[50:51], v[50:51]
	v_pk_mul_f32 v[52:53], v[52:53], v[52:53]
	v_pk_mul_f32 v[54:55], v[54:55], v[54:55]
	v_cvt_pk_bf16_f32 v52, v52, v53
	v_cvt_pk_bf16_f32 v53, v54, v55
	v_cvt_pk_bf16_f32 v54, v48, v49
	v_cvt_pk_bf16_f32 v55, v50, v51
	global_store_dwordx4 v154, v[52:55], s[10:11] offset:256
	v_max_f32_e32 v40, 0, v40
	v_max_f32_e32 v41, 0, v41
	v_max_f32_e32 v42, 0, v42
	v_max_f32_e32 v43, 0, v43
	v_max_f32_e32 v44, 0, v44
	v_max_f32_e32 v45, 0, v45
	v_max_f32_e32 v46, 0, v46
	v_max_f32_e32 v47, 0, v47
	v_pk_mul_f32 v[40:41], v[40:41], v[40:41]
	v_pk_mul_f32 v[42:43], v[42:43], v[42:43]
	v_pk_mul_f32 v[44:45], v[44:45], v[44:45]
	v_pk_mul_f32 v[46:47], v[46:47], v[46:47]
	v_cvt_pk_bf16_f32 v44, v44, v45
	v_cvt_pk_bf16_f32 v45, v46, v47
	v_cvt_pk_bf16_f32 v46, v40, v41
	v_cvt_pk_bf16_f32 v47, v42, v43
	global_store_dwordx4 v155, v[44:47], s[10:11]
	v_max_f32_e32 v32, 0, v32
	v_max_f32_e32 v33, 0, v33
	v_max_f32_e32 v34, 0, v34
	v_max_f32_e32 v35, 0, v35
	v_max_f32_e32 v36, 0, v36
	v_max_f32_e32 v37, 0, v37
	v_max_f32_e32 v38, 0, v38
	v_max_f32_e32 v39, 0, v39
	v_pk_mul_f32 v[32:33], v[32:33], v[32:33]
	v_pk_mul_f32 v[34:35], v[34:35], v[34:35]
	v_pk_mul_f32 v[36:37], v[36:37], v[36:37]
	v_pk_mul_f32 v[38:39], v[38:39], v[38:39]
	v_cvt_pk_bf16_f32 v36, v36, v37
	v_cvt_pk_bf16_f32 v37, v38, v39
	v_cvt_pk_bf16_f32 v38, v32, v33
	v_cvt_pk_bf16_f32 v39, v34, v35
	global_store_dwordx4 v155, v[36:39], s[10:11] offset:256
	v_max_f32_e32 v24, 0, v24
	v_max_f32_e32 v25, 0, v25
	v_max_f32_e32 v26, 0, v26
	v_max_f32_e32 v27, 0, v27
	v_max_f32_e32 v28, 0, v28
	v_max_f32_e32 v29, 0, v29
	v_max_f32_e32 v30, 0, v30
	v_max_f32_e32 v31, 0, v31
	v_pk_mul_f32 v[24:25], v[24:25], v[24:25]
	v_pk_mul_f32 v[26:27], v[26:27], v[26:27]
	v_pk_mul_f32 v[28:29], v[28:29], v[28:29]
	v_pk_mul_f32 v[30:31], v[30:31], v[30:31]
	v_cvt_pk_bf16_f32 v28, v28, v29
	v_cvt_pk_bf16_f32 v29, v30, v31
	v_cvt_pk_bf16_f32 v30, v24, v25
	v_cvt_pk_bf16_f32 v31, v26, v27
	global_store_dwordx4 v156, v[28:31], s[10:11]
	v_max_f32_e32 v16, 0, v16
	v_max_f32_e32 v17, 0, v17
	v_max_f32_e32 v18, 0, v18
	v_max_f32_e32 v19, 0, v19
	v_max_f32_e32 v20, 0, v20
	v_max_f32_e32 v21, 0, v21
	v_max_f32_e32 v22, 0, v22
	v_max_f32_e32 v23, 0, v23
	v_pk_mul_f32 v[16:17], v[16:17], v[16:17]
	v_pk_mul_f32 v[18:19], v[18:19], v[18:19]
	v_pk_mul_f32 v[20:21], v[20:21], v[20:21]
	v_pk_mul_f32 v[22:23], v[22:23], v[22:23]
	v_cvt_pk_bf16_f32 v20, v20, v21
	v_cvt_pk_bf16_f32 v21, v22, v23
	v_cvt_pk_bf16_f32 v22, v16, v17
	v_cvt_pk_bf16_f32 v23, v18, v19
	global_store_dwordx4 v156, v[20:23], s[10:11] offset:256
	v_max_f32_e32 v8, 0, v8
	v_max_f32_e32 v9, 0, v9
	v_max_f32_e32 v10, 0, v10
	v_max_f32_e32 v11, 0, v11
	v_max_f32_e32 v12, 0, v12
	v_max_f32_e32 v13, 0, v13
	v_max_f32_e32 v14, 0, v14
	v_max_f32_e32 v15, 0, v15
	v_pk_mul_f32 v[8:9], v[8:9], v[8:9]
	v_pk_mul_f32 v[10:11], v[10:11], v[10:11]
	v_pk_mul_f32 v[12:13], v[12:13], v[12:13]
	v_pk_mul_f32 v[14:15], v[14:15], v[14:15]
	v_cvt_pk_bf16_f32 v12, v12, v13
	v_cvt_pk_bf16_f32 v13, v14, v15
	v_cvt_pk_bf16_f32 v14, v8, v9
	v_cvt_pk_bf16_f32 v15, v10, v11
	global_store_dwordx4 v157, v[12:15], s[10:11]
	v_max_f32_e32 v0, 0, v0
	v_max_f32_e32 v1, 0, v1
	v_max_f32_e32 v2, 0, v2
	v_max_f32_e32 v3, 0, v3
	v_max_f32_e32 v4, 0, v4
	v_max_f32_e32 v5, 0, v5
	v_max_f32_e32 v6, 0, v6
	v_max_f32_e32 v7, 0, v7
	v_pk_mul_f32 v[0:1], v[0:1], v[0:1]
	v_pk_mul_f32 v[2:3], v[2:3], v[2:3]
	v_pk_mul_f32 v[4:5], v[4:5], v[4:5]
	v_pk_mul_f32 v[6:7], v[6:7], v[6:7]
	v_cvt_pk_bf16_f32 v4, v4, v5
	v_cvt_pk_bf16_f32 v5, v6, v7
	v_cvt_pk_bf16_f32 v6, v0, v1
	v_cvt_pk_bf16_f32 v7, v2, v3
	global_store_dwordx4 v157, v[4:7], s[10:11] offset:256
	s_cbranch_vccz .LBB0_428
	s_waitcnt vmcnt(0)
	s_setprio 0
	s_cmpk_gt_u32 s46, 0xff
	s_cbranch_scc1 .LBB0_437
	s_barrier

; __device__ __forceinline__ void xcd_barrier(const XcdBarrier& b) {
;     asm volatile("s_waitcnt vmcnt(0)" ::: "memory");
;     __syncthreads();
;     if (threadIdx.x == 0) {
;         unsigned* bar = b.bar;
;         __builtin_amdgcn_s_waitcnt(0);
;         unsigned nloc = b.st[0], nx = b.st[1];
;         if (nloc == 0u) { xcd_barrier_complete(bar, b.x, nloc, nx); b.st[0] = nloc; b.st[1] = nx; }
.LBB0_438:
	s_nop 0
	s_nop 0
	s_nop 0
	s_nop 0
	s_nop 0
	s_nop 0
	s_nop 0
	s_nop 0
	s_nop 0
	s_nop 0
	s_nop 0
	s_nop 0
	s_nop 0
	s_nop 0
	s_nop 0
	s_nop 0
	s_nop 0
	s_nop 0
	s_cmp_gt_i32 s31, 5
	s_cselect_b64 s[0:1], -1, 0
	s_and_b64 s[4:5], s[6:7], s[0:1]
	s_andn2_b64 vcc, exec, s[4:5]
	s_cbranch_vccnz .LBB0_488
	s_waitcnt vmcnt(0)
	s_waitcnt vmcnt(0) lgkmcnt(0)
	s_barrier
	s_and_saveexec_b64 s[4:5], s[8:9]
	s_cbranch_execz .LBB0_487
	s_add_i32 s6, 0, 0x25ff0
	v_mov_b32_e32 v0, s6
	s_waitcnt vmcnt(0) expcnt(0) lgkmcnt(0)
	ds_read_b32 v2, v0
	s_add_i32 s6, 0, 0x25ff4
	v_mov_b32_e32 v0, s6
	ds_read_b32 v0, v0
	s_waitcnt lgkmcnt(1)
	v_cmp_ne_u32_e32 vcc, 0, v2
	s_cbranch_vccnz .LBB0_455
	s_load_dwordx2 s[10:11], s[52:53], 0x4
	s_add_u32 s6, s28, 0x3e800200
	s_addc_u32 s7, s29, 0
	s_add_u32 s8, s28, 0x3e800400
	s_addc_u32 s9, s29, 0
	s_waitcnt lgkmcnt(0)
	s_mul_i32 s31, s10, s3
	s_add_u32 s10, s28, 0x3e800500
	s_mul_i32 s31, s31, s11
	s_addc_u32 s11, s29, 0
	s_add_u32 s12, s28, 0x3e800600
	s_addc_u32 s13, s29, 0
	s_add_u32 s14, s28, 0x3e800700
	s_addc_u32 s15, s29, 0
	s_add_u32 s16, s28, 0x3e800800
	s_addc_u32 s17, s29, 0
	s_add_u32 s18, s28, 0x3e800900
	s_addc_u32 s19, s29, 0
	s_add_u32 s20, s28, 0x3e800a00
	s_addc_u32 s21, s29, 0
	s_add_u32 s22, s28, 0x3e800b00
	s_addc_u32 s23, s29, 0
	s_add_u32 s24, s28, 0x3e800c00
	s_addc_u32 s25, s29, 0
	s_add_u32 s36, s28, 0x3e800d00
	s_addc_u32 s37, s29, 0
	s_add_u32 s38, s28, 0x3e800e00
	s_addc_u32 s39, s29, 0
	s_add_u32 s40, s28, 0x3e800f00
	s_addc_u32 s41, s29, 0
	s_add_u32 s42, s28, 0x3e801000
	s_addc_u32 s43, s29, 0
	s_add_u32 s44, s28, 0x3e801100
	s_addc_u32 s45, s29, 0
	s_add_u32 s46, s28, 0x3e801200
	s_addc_u32 s47, s29, 0
	s_add_u32 s48, s28, 0x3e801300
	s_addc_u32 s49, s29, 0
	s_mov_b32 s56, 1
	v_mov_b32_e32 v16, 0
	s_branch .LBB0_443
